# static s_setprio 1 for waves 4-7 during the attention item loop (reset to 0 after)
# baseline (speedup 1.0000x reference)
; __device__ __forceinline__ void attn_items(const Ctx& C, const PV& P, int layer, int ctr_idx, unsigned char* smem) {
;     ...
;     const float lam_init = layer == 0 ? 0.2f : (0.8f - 0.6f * 0.7408182206817179f);
;     float lam_full;
;     {
;         const float* lm = P.inp(24) + (size_t)layer * 256;
;         float s1 = 0.f, s2 = 0.f;
;         for (int i = 0; i < 64; ++i) { s1 += lm[i] * lm[64 + i]; s2 += lm[128 + i] * lm[192 + i]; }
;         lam_full = expf(s1) - expf(s2) + lam_init;
;     }
;     const float* normg = P.inp(25) + (size_t)layer * 128;
;     unsigned* ctr = (unsigned*)(P.ws + WS_CTR) + ctr_idx * 16;
;     volatile unsigned* bc = (volatile unsigned*)(smem + 131088);
;     for (;;) {
;         __syncthreads();
;         if (tid == 0) *bc = atomicAdd(ctr, 1u);
;         __syncthreads();
;         const int item = (int)*bc;
;         if (item >= 1280) break;
;         int sq, h, qb;
;         if (item < 256) { sq = 0; h = item >> 6; qb = item & 63; } else { const int i2 = item - 256; sq = 1 + (i2 >> 7); h = (i2 >> 5) & 3; qb = i2 & 31; }
;         const int lt0 = seqbase_of(sq), S = seqlen_of(sq);
;         const bf16_t* Qb = Qall + (size_t)lt0 * 512; const bf16_t* Kb = Kall + (size_t)lt0 * 512; const bf16_t* Vb = Vall + (size_t)lt0 * 512 + (size_t)h * 128 * S;
;         const int q0 = qb * 128 + rg * 32;
;         bf16x8 bq[2][2];
; #pragma unroll
;         for (int qs = 0; qs < 2; ++qs)
; #pragma unroll
;             for (int ks = 0; ks < 2; ++ks) bq[qs][ks] = *(const bf16x8*)(Qb + ((size_t)(h * 2 + comp) * S + q0 + qs * 16 + fr) * 64 + ks * 32 + fq * 8);
;         float m_run[2] = {-1e30f, -1e30f}, l_run[2] = {0.f, 0.f};
;         f32x4 O[8][2];
; #pragma unroll
;         for (int a = 0; a < 8; ++a) { O[a][0] = (f32x4){0.f, 0.f, 0.f, 0.f}; O[a][1] = (f32x4){0.f, 0.f, 0.f, 0.f}; }
;         u32x4 rk[2], rv[2];
;         const int lrow = tid >> 3, lkc = (tid & 7) * 8;
.LBB0_557:
	s_add_u32 s12, s4, s2
	s_addc_u32 s13, s5, s3
	global_load_dwordx4 v[2:5], v133, s[12:13] offset:48
	global_load_dwordx4 v[6:9], v133, s[12:13] offset:32
	global_load_dwordx4 v[10:13], v133, s[12:13] offset:16
	global_load_dwordx4 v[14:17], v133, s[12:13]
	global_load_dwordx4 v[18:21], v133, s[12:13] offset:304
	global_load_dwordx4 v[22:25], v133, s[12:13] offset:288
	global_load_dwordx4 v[26:29], v133, s[12:13] offset:272
	global_load_dwordx4 v[30:33], v133, s[12:13] offset:256
	global_load_dwordx4 v[34:37], v133, s[12:13] offset:560
	global_load_dwordx4 v[38:41], v133, s[12:13] offset:544
	global_load_dwordx4 v[42:45], v133, s[12:13] offset:528
	global_load_dwordx4 v[46:49], v133, s[12:13] offset:512
	global_load_dwordx4 v[50:53], v133, s[12:13] offset:816
	global_load_dwordx4 v[54:57], v133, s[12:13] offset:800
	global_load_dwordx4 v[58:61], v133, s[12:13] offset:784
	global_load_dwordx4 v[62:65], v133, s[12:13] offset:768
	s_add_u32 s2, s2, 64
	s_addc_u32 s3, s3, 0
	s_cmpk_eq_i32 s2, 0x100
	s_waitcnt vmcnt(0)
	v_mov_b32_e32 v66, v14
	v_mov_b32_e32 v14, v16
	v_mov_b32_e32 v16, v26
	v_mov_b32_e32 v68, v30
	v_mov_b32_e32 v30, v32
	v_mov_b32_e32 v67, v46
	v_mov_b32_e32 v46, v15
	v_mov_b32_e32 v15, v48
	v_mov_b32_e32 v48, v17
	v_mov_b32_e32 v69, v62
	v_pk_fma_f32 v[0:1], v[66:67], v[68:69], v[0:1]
	v_mov_b32_e32 v62, v31
	v_pk_fma_f32 v[0:1], v[46:47], v[62:63], v[0:1]
	v_mov_b32_e32 v31, v64
	v_pk_fma_f32 v[0:1], v[14:15], v[30:31], v[0:1]
	v_mov_b32_e32 v64, v33
	v_pk_fma_f32 v[0:1], v[48:49], v[64:65], v[0:1]
	v_mov_b32_e32 v14, v10
	v_mov_b32_e32 v15, v42
	v_mov_b32_e32 v17, v58
	v_pk_fma_f32 v[0:1], v[14:15], v[16:17], v[0:1]
	v_mov_b32_e32 v42, v11
	v_mov_b32_e32 v58, v27
	v_pk_fma_f32 v[0:1], v[42:43], v[58:59], v[0:1]
	v_mov_b32_e32 v10, v12
	v_mov_b32_e32 v11, v44
	v_mov_b32_e32 v14, v28
	v_mov_b32_e32 v15, v60
	v_pk_fma_f32 v[0:1], v[10:11], v[14:15], v[0:1]
	v_mov_b32_e32 v44, v13
	v_mov_b32_e32 v60, v29
	v_pk_fma_f32 v[0:1], v[44:45], v[60:61], v[0:1]
	v_mov_b32_e32 v10, v6
	v_mov_b32_e32 v11, v38
	v_mov_b32_e32 v12, v22
	v_mov_b32_e32 v13, v54
	v_pk_fma_f32 v[0:1], v[10:11], v[12:13], v[0:1]
	v_mov_b32_e32 v38, v7
	v_mov_b32_e32 v54, v23
	v_pk_fma_f32 v[0:1], v[38:39], v[54:55], v[0:1]
	v_mov_b32_e32 v6, v8
	v_mov_b32_e32 v7, v40
	v_mov_b32_e32 v10, v24
	v_mov_b32_e32 v11, v56
	v_pk_fma_f32 v[0:1], v[6:7], v[10:11], v[0:1]
	v_mov_b32_e32 v40, v9
	v_mov_b32_e32 v56, v25
	v_pk_fma_f32 v[0:1], v[40:41], v[56:57], v[0:1]
	v_mov_b32_e32 v6, v2
	v_mov_b32_e32 v7, v34
	v_mov_b32_e32 v8, v18
	v_mov_b32_e32 v9, v50
	v_pk_fma_f32 v[0:1], v[6:7], v[8:9], v[0:1]
	v_mov_b32_e32 v34, v3
	v_mov_b32_e32 v50, v19
	v_pk_fma_f32 v[0:1], v[34:35], v[50:51], v[0:1]
	v_mov_b32_e32 v2, v4
	v_mov_b32_e32 v3, v36
	v_mov_b32_e32 v6, v20
	v_mov_b32_e32 v7, v52
	v_pk_fma_f32 v[0:1], v[2:3], v[6:7], v[0:1]
	v_mov_b32_e32 v36, v5
	v_mov_b32_e32 v52, v21
	v_pk_fma_f32 v[0:1], v[36:37], v[52:53], v[0:1]
	s_cbranch_scc0 .LBB0_557
	s_add_i32 s2, s91, 14
	s_and_b32 s4, s2, 0xff
	s_add_u32 s2, s66, 0x28d8c000
	s_addc_u32 s3, s67, 0
	v_mul_f32_e32 v2, 0x3fb8aa3b, v0
	s_cmp_lt_u32 s4, 29
	v_rndne_f32_e32 v3, v2
	s_mov_b32 s4, 0x3fb8aa3b
	v_sub_f32_e32 v4, v2, v3
	v_fma_f32 v2, v0, s4, -v2
	v_fmac_f32_e32 v2, 0x32a5705f, v0
	v_add_f32_e32 v2, v4, v2
	v_exp_f32_e32 v2, v2
	v_cvt_i32_f32_e32 v3, v3
	s_cselect_b64 vcc, -1, 0
	v_mov_b32_e32 v5, 0x3eb60549
	v_mov_b32_e32 v6, 0x3e4ccccd
	v_ldexp_f32 v2, v2, v3
	v_mul_f32_e32 v3, 0x3fb8aa3b, v1
	v_cndmask_b32_e32 v5, v5, v6, vcc
	v_rndne_f32_e32 v6, v3
	v_sub_f32_e32 v7, v3, v6
	v_fma_f32 v3, v1, s4, -v3
	v_fmac_f32_e32 v3, 0x32a5705f, v1
	v_add_f32_e32 v3, v7, v3
	v_exp_f32_e32 v3, v3
	v_cvt_i32_f32_e32 v6, v6
	s_mov_b32 s4, 0xc2ce8ed0
	v_cmp_ngt_f32_e32 vcc, s4, v0
	s_mov_b32 s6, 0x42b17218
	v_mov_b32_e32 v7, 0x7f800000
	v_cndmask_b32_e32 v2, 0, v2, vcc
	v_cmp_nlt_f32_e32 vcc, s6, v0
	s_add_u32 s12, s66, 0x2658c000
	s_addc_u32 s13, s67, 0
	v_cndmask_b32_e32 v0, v7, v2, vcc
	v_cmp_ngt_f32_e32 vcc, s4, v1
	s_load_dwordx2 s[4:5], s[24:25], 0xc8
	v_ldexp_f32 v2, v3, v6
	v_cndmask_b32_e32 v2, 0, v2, vcc
	v_cmp_nlt_f32_e32 vcc, s6, v1
	v_readlane_b32 s6, v255, 26
	s_add_u32 s20, s66, 0x37d8c000
	v_readlane_b32 s7, v255, 27
	s_addc_u32 s21, s67, 0
	s_lshl_b64 s[6:7], s[6:7], 9
	s_waitcnt lgkmcnt(0)
	s_add_u32 s4, s4, s6
	s_addc_u32 s5, s5, s7
	s_lshl_b32 s6, s90, 5
	s_lshl_b32 s7, s10, 4
	s_add_i32 s6, s7, s6
	s_ashr_i32 s7, s6, 31
	s_lshl_b64 s[6:7], s[6:7], 2
	v_cndmask_b32_e32 v1, v7, v2, vcc
	s_add_u32 s6, s66, s6
	v_bfe_u32 v4, v199, 4, 2
	v_sub_f32_e32 v0, v0, v1
	s_addc_u32 s7, s67, s7
	v_add_f32_e32 v130, v5, v0
	s_add_u32 s34, s6, 0x3f71f700
	v_ashrrev_i32_e32 v0, 2, v144
	v_lshlrev_b32_e32 v132, 4, v4
	s_addc_u32 s35, s7, 0
	v_and_b32_e32 v201, 0xffffffe0, v0
	v_lshl_add_u64 v[0:1], s[66:67], 0, v[132:133]
	s_mov_b64 s[6:7], 0x23d8c000
	v_lshlrev_b32_e32 v200, 3, v199
	v_lshl_add_u64 v[146:147], v[0:1], 0, s[6:7]
	v_ashrrev_i32_e32 v148, 3, v144
	v_and_b32_e32 v0, 56, v200
	s_movk_i32 s7, 0x90
	v_mul_lo_u32 v1, v148, s7
	v_lshlrev_b32_e32 v2, 1, v0
	s_movk_i32 s6, 0xff
	v_and_b32_e32 v128, 15, v199
	v_add3_u32 v204, 0, v1, v2
	v_cmp_lt_u32_e64 s[42:43], s6, v144
	v_and_b32_e32 v2, 0xffffff00, v144
	s_movk_i32 s6, 0x100
	v_lshlrev_b32_e32 v3, 3, v4
	v_cmp_eq_u32_e64 s[44:45], s6, v2
	v_mad_u32_u24 v2, v128, s7, 0
	v_add_u32_e32 v6, 0xd800, v2
	v_add_u32_e32 v205, v2, v3
	v_and_b32_e32 v2, 64, v144
	v_bfe_u32 v151, v144, 6, 1
	v_cmp_ne_u32_e64 s[48:49], 0, v2
	v_lshlrev_b32_e32 v2, 2, v4
	s_mov_b32 s6, 0x1ffff80
	v_lshl_or_b32 v1, v151, 6, v128
	v_and_or_b32 v4, v144, s6, v2
	v_add_u32_e32 v152, 64, v148
	v_mul_u32_u24_e32 v1, 0x90, v1
	v_sub_f32_e32 v206, 1.0, v5
	v_lshlrev_b32_e32 v4, 7, v4
	v_lshlrev_b32_e32 v5, 2, v128
	v_cmp_eq_u32_e64 s[40:41], 0, v144
	v_ashrrev_i32_e32 v202, 9, v144
	v_and_b32_e32 v150, 63, v148
	v_mov_b32_e32 v129, v133
	v_ashrrev_i32_e32 v149, 31, v148
	v_ashrrev_i32_e32 v203, 6, v152
	v_ashrrev_i32_e32 v153, 31, v152
	v_cmp_eq_u32_e64 s[46:47], 0, v151
	v_add3_u32 v207, 0, v4, v5
	v_lshl_add_u64 v[154:155], s[4:5], 0, v[132:133]
	v_mov_b32_e32 v131, v130
	v_add3_u32 v208, 0, v1, v132
	s_mov_b64 s[52:53], 0
	v_lshlrev_b32_e32 v156, 1, v0
	v_add_u32_e32 v209, v6, v3
	v_lshlrev_b32_e32 v158, 1, v2
	s_cmpk_lt_u32 s27, 0x100
	s_cbranch_scc1 .Lattn_prio_done
	s_setprio 1
.Lattn_prio_done:
	s_branch .LBB0_561
.LBB0_559:
	s_or_b64 exec, exec, s[50:51]
	s_xor_b64 s[50:51], exec, -1

; __device__ __forceinline__ void attn_items(const Ctx& C, const PV& P, int layer, int ctr_idx, unsigned char* smem) {
;     ...
;     __syncthreads();
; }
; __device__ __forceinline__ void fft_items(const Ctx& C, const PV& P, unsigned char* smem) {
;     unsigned char* R = P.ws + WS_R;
;     typedef f16 f16x2 __attribute__((ext_vector_type(2)));
;     const f16x2* Zall = (const f16x2*)(R + R_ZC);
;     bf16_t* yf = (bf16_t*)(R + R_YB) + 2 * SZ512;
;     const float2* tw = (const float2*)(P.ws + WS_TW);
;     float2* sm = (float2*)smem;
;     const int tid = C.tid;
;     for (int item = C.bid; item < NSEQ * 256; item += C.nblk) {
;         const int sq = item >> 8, col = item & 255, g = col >> 6, cc = col & 63;
;         const int lt0 = seqbase_of(sq), S = seqlen_of(sq), lg = sq == 0 ? 13 : 12;
;         const f16x2* z = Zall + (size_t)lt0 * 256 + (size_t)col * S;
.LBB0_599:
	s_or_b64 exec, exec, s[52:53]
	s_setprio 0
	s_cmpk_gt_i32 s87, 0x8ff
	s_barrier
	s_cbranch_scc1 .LBB0_625
	s_add_u32 s4, s66, 0x3a58c000
	v_lshl_add_u64 v[0:1], v[144:145], 2, s[66:67]
	s_mov_b64 s[6:7], 0x3058c000
	s_addc_u32 s5, s67, 0
	v_lshl_add_u64 v[0:1], v[0:1], 0, s[6:7]
	v_readlane_b32 s6, v255, 18
	s_add_u32 s2, s66, 0x7040000
	s_addc_u32 s3, s67, 0
	v_sub_u32_e32 v4, s6, v199
	v_readlane_b32 s6, v255, 15
	s_nop 1
	v_add_u32_e32 v5, s6, v200
	s_mov_b32 s6, s87
	s_branch .LBB0_602
